# D latent tile: 31-add row-sum chain replaced by 15 packed f32 adds on a register pair plus one final add
# baseline (speedup 1.0000x reference)
; #define LAS __attribute__((address_space(3)))
; DI unsigned pk2(float lo, float hi) { f32x2 v = {lo, hi}; bf16x2_t b = __builtin_convertvector(v, bf16x2_t); return __builtin_bit_cast(unsigned, b); }
; DI float fast_exp2(float x) { return __builtin_amdgcn_exp2f(x); }
; DI void attn_unit_d32(const Ctx& C, const bf16_t* __restrict__ Z, bf16_t* __restrict__ Y, int b, int qsel, int hsel, bool ctxq, float lam, float post_scale, const float* subln, const float mref) {
;     ...
;         const LAS bf16_t* Ks = lds16 + ((t & 1) * AT_BUF) / 2 + 64 * sm; const LAS bf16_t* Vt = lds16 + ((t & 1) * AT_BUF + AT_VT) / 2;
;         f32x16 st[2];
; #pragma unroll
;         for (int kb = 0; kb < 2; ++kb) {
; #pragma unroll
;             for (int r = 0; r < 16; ++r) st[kb][r] = negm;
; #pragma unroll
;             for (int ks = 0; ks < 4; ++ks) { const bf16x8 a = *(const LAS bf16x8*)(Ks + (32 * kb + l31) * KST + 16 * ks + 8 * hh);
;                 st[kb] = __builtin_amdgcn_mfma_f32_32x32x16_bf16(a, qf[ks], st[kb], 0, 0, 0); } }
;         bf16x8 pf[2][2]; float ps = 0.f;
; #pragma unroll
;         for (int kb = 0; kb < 2; ++kb) {
; #pragma unroll
;             for (int r = 0; r < 16; ++r) { const float p = fast_exp2(st[kb][r]); st[kb][r] = p; ps += p; }
; #pragma unroll
;             for (int s = 0; s < 2; ++s) { u32x4 pw; pw.x = pk2(st[kb][8 * s], st[kb][8 * s + 1]); pw.y = pk2(st[kb][8 * s + 2], st[kb][8 * s + 3]); pw.z = pk2(st[kb][8 * s + 4], st[kb][8 * s + 5]); pw.w = pk2(st[kb][8 * s + 6], st[kb][8 * s + 7]);
;                 pf[kb][s] = __builtin_bit_cast(bf16x8, pw); } }
;         lsum += ps;
; #pragma unroll
;         for (int d = 0; d < 4; ++d)
; #pragma unroll
;             for (int kb = 0; kb < 2; ++kb)
; #pragma unroll
;                 for (int s = 0; s < 2; ++s) { const LAS bf16_t* vp = Vt + (32 * d + l31) * VST + 32 * kb + 16 * s + 4 * hh;
;                     const u32x2 lo = *(const LAS u32x2*)vp, hi = *(const LAS u32x2*)(vp + 8);
;                     u32x4 av; av.x = lo.x; av.y = lo.y; av.z = hi.x; av.w = hi.y;
;                     o[d] = __builtin_amdgcn_mfma_f32_32x32x16_bf16(__builtin_bit_cast(bf16x8, av), pf[kb][s], o[d], 0, 0, 0); }
.LBB0_399:
.LBB0_407:
	s_add_i32 s0, s23, 1
	s_bitcmp1_b32 s23, 0
	s_cselect_b32 s1, 0x9000, 0
	s_lshl_b32 s24, s18, 1
	s_add_i32 s24, s1, s24
	v_add3_u32 v194, s24, v183, v184
	ds_read_b128 v[84:87], v194
	ds_read_b128 v[88:91], v194 offset:32
	ds_read_b128 v[92:95], v194 offset:64
	ds_read_b128 v[96:99], v194 offset:96
	ds_read_b128 v[214:217], v194 offset:8704
	ds_read_b128 v[218:221], v194 offset:8736
	ds_read_b128 v[222:225], v194 offset:8768
	ds_read_b128 v[240:243], v194 offset:8800
	v_add3_u32 v195, s1, v183, v185
	ds_read_b128 v[244:247], v195 offset:17408
	ds_read_b128 v[210:213], v195 offset:17440
	s_waitcnt lgkmcnt(9)
	v_mfma_f32_32x32x16_bf16 v[100:115], v[84:87], v[116:119], v[4:19]
	s_waitcnt lgkmcnt(8)
	v_mfma_f32_32x32x16_bf16 v[100:115], v[88:91], v[120:123], v[100:115]
	s_waitcnt lgkmcnt(7)
	v_mfma_f32_32x32x16_bf16 v[100:115], v[92:95], v[124:127], v[100:115]
	s_waitcnt lgkmcnt(6)
	v_mfma_f32_32x32x16_bf16 v[100:115], v[96:99], v[128:131], v[100:115]
	s_waitcnt lgkmcnt(5)
	v_mfma_f32_32x32x16_bf16 v[84:99], v[214:217], v[116:119], v[4:19]
	ds_read_b128 v[214:217], v195 offset:22016
	s_waitcnt lgkmcnt(5)
	v_mfma_f32_32x32x16_bf16 v[84:99], v[218:221], v[120:123], v[84:99]
	ds_read_b128 v[218:221], v195 offset:22048
	s_waitcnt lgkmcnt(5)
	v_mfma_f32_32x32x16_bf16 v[84:99], v[222:225], v[124:127], v[84:99]
	ds_read_b128 v[222:225], v195 offset:26624
	s_waitcnt lgkmcnt(5)
	v_mfma_f32_32x32x16_bf16 v[84:99], v[240:243], v[128:131], v[84:99]
	ds_read_b128 v[240:243], v195 offset:26656
	v_exp_f32_e32 v100, v100
	v_exp_f32_e32 v101, v101
	v_exp_f32_e32 v102, v102
	v_exp_f32_e32 v103, v103
	v_exp_f32_e32 v104, v104
	v_pk_add_f32 v[202:203], v[100:101], v[102:103]
	v_exp_f32_e32 v105, v105
	v_exp_f32_e32 v106, v106
	v_pk_add_f32 v[202:203], v[202:203], v[104:105]
	v_exp_f32_e32 v107, v107
	v_exp_f32_e32 v108, v108
	v_pk_add_f32 v[202:203], v[202:203], v[106:107]
	v_exp_f32_e32 v109, v109
	v_exp_f32_e32 v110, v110
	v_pk_add_f32 v[202:203], v[202:203], v[108:109]
	v_exp_f32_e32 v111, v111
	v_exp_f32_e32 v112, v112
	v_pk_add_f32 v[202:203], v[202:203], v[110:111]
	v_exp_f32_e32 v113, v113
	v_exp_f32_e32 v114, v114
	v_pk_add_f32 v[202:203], v[202:203], v[112:113]
	v_exp_f32_e32 v115, v115
	v_cvt_pk_bf16_f32 v100, v100, v101
	v_pk_add_f32 v[202:203], v[202:203], v[114:115]
	v_cvt_pk_bf16_f32 v101, v102, v103
	v_cvt_pk_bf16_f32 v102, v104, v105
	v_cvt_pk_bf16_f32 v103, v106, v107
	v_cvt_pk_bf16_f32 v104, v108, v109
	v_cvt_pk_bf16_f32 v105, v110, v111
	v_cvt_pk_bf16_f32 v106, v112, v113
	v_cvt_pk_bf16_f32 v107, v114, v115
	ds_read_b128 v[108:111], v195 offset:31232
	ds_read_b128 v[112:115], v195 offset:31264
	s_waitcnt lgkmcnt(7)
	v_mfma_f32_32x32x16_bf16 v[68:83], v[244:247], v[100:103], v[68:83]
	ds_read_b128 v[244:247], v195 offset:17472
	v_exp_f32_e32 v84, v84
	v_exp_f32_e32 v85, v85
	v_exp_f32_e32 v86, v86
	v_pk_add_f32 v[202:203], v[202:203], v[84:85]
	s_waitcnt lgkmcnt(7)
	v_mfma_f32_32x32x16_bf16 v[68:83], v[210:213], v[104:107], v[68:83]
	ds_read_b128 v[210:213], v195 offset:17504
	v_exp_f32_e32 v87, v87
	v_exp_f32_e32 v88, v88
	v_pk_add_f32 v[202:203], v[202:203], v[86:87]
	v_exp_f32_e32 v89, v89
	s_waitcnt lgkmcnt(7)
	v_mfma_f32_32x32x16_bf16 v[52:67], v[214:217], v[100:103], v[52:67]
	ds_read_b128 v[214:217], v195 offset:22080
	v_exp_f32_e32 v90, v90
	v_pk_add_f32 v[202:203], v[202:203], v[88:89]
	v_exp_f32_e32 v91, v91
	s_waitcnt lgkmcnt(7)
	v_mfma_f32_32x32x16_bf16 v[52:67], v[218:221], v[104:107], v[52:67]
	ds_read_b128 v[218:221], v195 offset:22112
	v_exp_f32_e32 v92, v92
	v_pk_add_f32 v[202:203], v[202:203], v[90:91]
	v_exp_f32_e32 v93, v93
	v_exp_f32_e32 v94, v94
	s_waitcnt lgkmcnt(7)
	v_mfma_f32_32x32x16_bf16 v[36:51], v[222:225], v[100:103], v[36:51]
	ds_read_b128 v[222:225], v195 offset:26688
	v_pk_add_f32 v[202:203], v[202:203], v[92:93]
	v_exp_f32_e32 v95, v95
	v_exp_f32_e32 v96, v96
	v_pk_add_f32 v[202:203], v[202:203], v[94:95]
	s_waitcnt lgkmcnt(7)
	v_mfma_f32_32x32x16_bf16 v[36:51], v[240:243], v[104:107], v[36:51]
	ds_read_b128 v[240:243], v195 offset:26720
	v_exp_f32_e32 v97, v97
	v_exp_f32_e32 v98, v98
	v_pk_add_f32 v[202:203], v[202:203], v[96:97]
	v_exp_f32_e32 v99, v99
	s_waitcnt lgkmcnt(7)
	v_mfma_f32_32x32x16_bf16 v[20:35], v[108:111], v[100:103], v[20:35]
	ds_read_b128 v[108:111], v195 offset:31296
	v_cvt_pk_bf16_f32 v84, v84, v85
	v_pk_add_f32 v[202:203], v[202:203], v[98:99]
	v_cvt_pk_bf16_f32 v85, v86, v87
	v_cvt_pk_bf16_f32 v86, v88, v89
	s_waitcnt lgkmcnt(7)
	v_mfma_f32_32x32x16_bf16 v[20:35], v[112:115], v[104:107], v[20:35]
	ds_read_b128 v[112:115], v195 offset:31328
	v_cvt_pk_bf16_f32 v87, v90, v91
	v_cvt_pk_bf16_f32 v88, v92, v93
	v_cvt_pk_bf16_f32 v89, v94, v95
	v_cvt_pk_bf16_f32 v90, v96, v97
	v_cvt_pk_bf16_f32 v91, v98, v99
	v_add_f32_e32 v209, v202, v203
	s_cmp_gt_u32 s23, 34
	s_cbranch_scc1 .Ldt_plain
	s_bitcmp1_b32 s23, 0
	s_cbranch_scc0 .Ldt_even
